# A/B/retO epilogue loads de-serialised + retO PV chain LDS reads software-pipelined (on top of v26)
# speedup vs baseline: 1.0130x; 1.0050x over previous
.LBB0_113:
	s_add_u32 s0, s0, s34
	s_addc_u32 s1, s1, s35
	global_load_dword v11, v1, s[0:1] offset:4
	s_waitcnt lgkmcnt(0)
	v_add_f32_e32 v0, v0, v10
	v_fmamk_f32 v0, v0, 0x3c800000, v202
	v_cmp_gt_f32_e32 vcc, s74, v0
	v_mul_f32_e32 v10, 0x4b800000, v0
	v_lshl_add_u64 v[12:13], v[162:163], 0, s[84:85]
	v_cndmask_b32_e32 v0, v0, v10, vcc
	v_rsq_f32_e32 v0, v0
	v_mov_b64_e32 v[16:17], s[96:97]
	v_mad_u64_u32 v[16:17], s[0:1], v12, s38, v[16:17]
	v_mul_f32_e32 v10, 0x45800000, v0
	v_cndmask_b32_e32 v0, v0, v10, vcc
	s_lshl_b32 s10, s68, 1
	v_lshlrev_b32_e32 v14, 2, v219
	v_mov_b32_e32 v15, v1
	s_waitcnt vmcnt(0)
	v_mul_f32_e32 v10, v0, v11
	v_mov_b32_e32 v0, v17
	v_mad_u64_u32 v[22:23], s[0:1], v13, s38, v[0:1]
	v_mov_b32_e32 v17, v22
	v_lshl_add_u64 v[24:25], v[16:17], 0, s[10:11]
	v_lshlrev_b64 v[16:17], 4, v[12:13]
	v_and_b32_e32 v11, 0xffffffe0, v16
	v_lshlrev_b32_e32 v0, 6, v12
	s_add_u32 s0, s92, s82
	v_and_b32_e32 v17, 0x1ffffff, v17
	v_and_b32_e32 v0, 64, v0
	v_or_b32_e32 v16, s69, v11
	s_addc_u32 s1, s93, s83
	v_lshl_add_u64 v[22:23], s[94:95], 0, v[0:1]
	v_lshlrev_b64 v[12:13], 7, v[16:17]
	v_lshlrev_b32_e32 v0, 3, v219
	v_lshl_add_u64 v[28:29], v[22:23], 0, v[12:13]
	v_lshl_add_u64 v[12:13], v[24:25], 0, v[0:1]
	v_lshl_add_u64 v[14:15], v[14:15], 2, s[0:1]
	global_load_dwordx2 v[66:67], v[12:13], off offset:1536
	global_load_dwordx4 v[172:175], v[14:15], off offset:0
	global_load_dwordx2 v[68:69], v[12:13], off offset:1552
	global_load_dwordx4 v[176:179], v[14:15], off offset:32
	global_load_dwordx2 v[70:71], v[12:13], off offset:1568
	global_load_dwordx4 v[180:183], v[14:15], off offset:64
	global_load_dwordx2 v[72:73], v[12:13], off offset:1584
	global_load_dwordx4 v[184:187], v[14:15], off offset:96
	global_load_dwordx2 v[74:75], v[12:13], off offset:1600
	global_load_dwordx4 v[188:191], v[14:15], off offset:128
	global_load_dwordx2 v[76:77], v[12:13], off offset:1616
	global_load_dwordx4 v[192:195], v[14:15], off offset:160
	global_load_dwordx2 v[78:79], v[12:13], off offset:1632
	global_load_dwordx4 v[82:85], v[14:15], off offset:192
	global_load_dwordx2 v[80:81], v[12:13], off offset:1648
	global_load_dwordx4 v[86:89], v[14:15], off offset:224
	v_lshl_add_u64 v[28:29], v[28:29], 0, v[0:1]
	v_or_b32_e32 v16, s99, v11
	v_lshlrev_b64 v[16:17], 7, v[16:17]
	v_lshl_add_u64 v[16:17], v[22:23], 0, v[16:17]
	v_lshl_add_u64 v[26:27], v[16:17], 0, v[0:1]
	s_add_i32 s2, s2, 1
	s_mov_b64 s[0:1], 0
	v_mul_f32_e32 v90, v58, v10
	v_mul_f32_e32 v91, v59, v10
	v_mul_f32_e32 v92, v56, v10
	v_mul_f32_e32 v93, v57, v10
	s_waitcnt vmcnt(14)
	v_mul_f32_e32 v90, v90, v172
	v_mul_f32_e32 v91, v91, v173
	v_mul_f32_e32 v92, v92, v174
	v_mul_f32_e32 v93, v93, v175
	v_lshlrev_b32_e32 v94, 16, v66
	v_and_b32_e32 v95, 0xffff0000, v66
	v_lshlrev_b32_e32 v96, 16, v67
	v_and_b32_e32 v97, 0xffff0000, v67
	v_mul_f32_e32 v90, v90, v94
	v_mul_f32_e32 v91, v91, v95
	v_mul_f32_e32 v92, v92, v96
	v_mul_f32_e32 v93, v93, v97
	v_cvt_pk_bf16_f32 v66, v90, v91
	v_cvt_pk_bf16_f32 v67, v92, v93
	global_store_dwordx2 v[28:29], v[66:67], off
	v_mul_f32_e32 v90, v54, v10
	v_mul_f32_e32 v91, v55, v10
	v_mul_f32_e32 v92, v52, v10
	v_mul_f32_e32 v93, v53, v10
	s_waitcnt vmcnt(13)
	v_mul_f32_e32 v90, v90, v176
	v_mul_f32_e32 v91, v91, v177
	v_mul_f32_e32 v92, v92, v178
	v_mul_f32_e32 v93, v93, v179
	v_lshlrev_b32_e32 v94, 16, v68
	v_and_b32_e32 v95, 0xffff0000, v68
	v_lshlrev_b32_e32 v96, 16, v69
	v_and_b32_e32 v97, 0xffff0000, v69
	v_mul_f32_e32 v90, v90, v94
	v_mul_f32_e32 v91, v91, v95
	v_mul_f32_e32 v92, v92, v96
	v_mul_f32_e32 v93, v93, v97
	v_cvt_pk_bf16_f32 v68, v90, v91
	v_cvt_pk_bf16_f32 v69, v92, v93
	global_store_dwordx2 v[28:29], v[68:69], off offset:16
	v_mul_f32_e32 v90, v50, v10
	v_mul_f32_e32 v91, v51, v10
	v_mul_f32_e32 v92, v42, v10
	v_mul_f32_e32 v93, v43, v10
	s_waitcnt vmcnt(12)
	v_mul_f32_e32 v90, v90, v180
	v_mul_f32_e32 v91, v91, v181
	v_mul_f32_e32 v92, v92, v182
	v_mul_f32_e32 v93, v93, v183
	v_lshlrev_b32_e32 v94, 16, v70
	v_and_b32_e32 v95, 0xffff0000, v70
	v_lshlrev_b32_e32 v96, 16, v71
	v_and_b32_e32 v97, 0xffff0000, v71
	v_mul_f32_e32 v90, v90, v94
	v_mul_f32_e32 v91, v91, v95
	v_mul_f32_e32 v92, v92, v96
	v_mul_f32_e32 v93, v93, v97
	v_cvt_pk_bf16_f32 v70, v90, v91
	v_cvt_pk_bf16_f32 v71, v92, v93
	global_store_dwordx2 v[28:29], v[70:71], off offset:32
	v_mul_f32_e32 v90, v40, v10
	v_mul_f32_e32 v91, v41, v10
	v_mul_f32_e32 v92, v38, v10
	v_mul_f32_e32 v93, v39, v10
	s_waitcnt vmcnt(11)
	v_mul_f32_e32 v90, v90, v184
	v_mul_f32_e32 v91, v91, v185
	v_mul_f32_e32 v92, v92, v186
	v_mul_f32_e32 v93, v93, v187
	v_lshlrev_b32_e32 v94, 16, v72
	v_and_b32_e32 v95, 0xffff0000, v72
	v_lshlrev_b32_e32 v96, 16, v73
	v_and_b32_e32 v97, 0xffff0000, v73
	v_mul_f32_e32 v90, v90, v94
	v_mul_f32_e32 v91, v91, v95
	v_mul_f32_e32 v92, v92, v96
	v_mul_f32_e32 v93, v93, v97
	v_cvt_pk_bf16_f32 v72, v90, v91
	v_cvt_pk_bf16_f32 v73, v92, v93
	global_store_dwordx2 v[28:29], v[72:73], off offset:48
	v_mul_f32_e32 v90, v36, v10
	v_mul_f32_e32 v91, v37, v10
	v_mul_f32_e32 v92, v34, v10
	v_mul_f32_e32 v93, v35, v10
	s_waitcnt vmcnt(10)
	v_mul_f32_e32 v90, v90, v188
	v_mul_f32_e32 v91, v91, v189
	v_mul_f32_e32 v92, v92, v190
	v_mul_f32_e32 v93, v93, v191
	v_lshlrev_b32_e32 v94, 16, v74
	v_and_b32_e32 v95, 0xffff0000, v74
	v_lshlrev_b32_e32 v96, 16, v75
	v_and_b32_e32 v97, 0xffff0000, v75
	v_mul_f32_e32 v90, v90, v94
	v_mul_f32_e32 v91, v91, v95
	v_mul_f32_e32 v92, v92, v96
	v_mul_f32_e32 v93, v93, v97
	v_cvt_pk_bf16_f32 v74, v90, v91
	v_cvt_pk_bf16_f32 v75, v92, v93
	global_store_dwordx2 v[26:27], v[74:75], off
	v_mul_f32_e32 v90, v20, v10
	v_mul_f32_e32 v91, v21, v10
	v_mul_f32_e32 v92, v18, v10
	v_mul_f32_e32 v93, v19, v10
	s_waitcnt vmcnt(9)
	v_mul_f32_e32 v90, v90, v192
	v_mul_f32_e32 v91, v91, v193
	v_mul_f32_e32 v92, v92, v194
	v_mul_f32_e32 v93, v93, v195
	v_lshlrev_b32_e32 v94, 16, v76
	v_and_b32_e32 v95, 0xffff0000, v76
	v_lshlrev_b32_e32 v96, 16, v77
	v_and_b32_e32 v97, 0xffff0000, v77
	v_mul_f32_e32 v90, v90, v94
	v_mul_f32_e32 v91, v91, v95
	v_mul_f32_e32 v92, v92, v96
	v_mul_f32_e32 v93, v93, v97
	v_cvt_pk_bf16_f32 v76, v90, v91
	v_cvt_pk_bf16_f32 v77, v92, v93
	global_store_dwordx2 v[26:27], v[76:77], off offset:16
	v_mul_f32_e32 v90, v8, v10
	v_mul_f32_e32 v91, v9, v10
	v_mul_f32_e32 v92, v6, v10
	v_mul_f32_e32 v93, v7, v10
	s_waitcnt vmcnt(8)
	v_mul_f32_e32 v90, v90, v82
	v_mul_f32_e32 v91, v91, v83
	v_mul_f32_e32 v92, v92, v84
	v_mul_f32_e32 v93, v93, v85
	v_lshlrev_b32_e32 v94, 16, v78
	v_and_b32_e32 v95, 0xffff0000, v78
	v_lshlrev_b32_e32 v96, 16, v79
	v_and_b32_e32 v97, 0xffff0000, v79
	v_mul_f32_e32 v90, v90, v94
	v_mul_f32_e32 v91, v91, v95
	v_mul_f32_e32 v92, v92, v96
	v_mul_f32_e32 v93, v93, v97
	v_cvt_pk_bf16_f32 v78, v90, v91
	v_cvt_pk_bf16_f32 v79, v92, v93
	global_store_dwordx2 v[26:27], v[78:79], off offset:32
	v_mul_f32_e32 v90, v4, v10
	v_mul_f32_e32 v91, v5, v10
	v_mul_f32_e32 v92, v2, v10
	v_mul_f32_e32 v93, v3, v10
	s_waitcnt vmcnt(7)
	v_mul_f32_e32 v90, v90, v86
	v_mul_f32_e32 v91, v91, v87
	v_mul_f32_e32 v92, v92, v88
	v_mul_f32_e32 v93, v93, v89
	v_lshlrev_b32_e32 v94, 16, v80
	v_and_b32_e32 v95, 0xffff0000, v80
	v_lshlrev_b32_e32 v96, 16, v81
	v_and_b32_e32 v97, 0xffff0000, v81
	v_mul_f32_e32 v90, v90, v94
	v_mul_f32_e32 v91, v91, v95
	v_mul_f32_e32 v92, v92, v96
	v_mul_f32_e32 v93, v93, v97
	v_cvt_pk_bf16_f32 v80, v90, v91
	v_cvt_pk_bf16_f32 v81, v92, v93
	global_store_dwordx2 v[26:27], v[80:81], off offset:48
	s_barrier

.LBB0_132:
	v_lshl_add_u64 v[2:3], s[6:7], 0, v[160:161]
	v_mov_b64_e32 v[4:5], s[82:83]
	v_mad_u64_u32 v[4:5], s[4:5], v2, s38, v[4:5]
	v_lshlrev_b32_e32 v0, 6, v2
	v_mad_i32_i24 v5, v3, s38, v5
	v_and_b32_e32 v0, 64, v0
	v_lshl_add_u64 v[4:5], s[0:1], 1, v[4:5]
	v_lshl_add_u64 v[6:7], s[30:31], 0, v[0:1]
	v_lshlrev_b32_e32 v0, 1, v170
	v_lshl_add_u64 v[4:5], v[4:5], 0, v[0:1]
	ds_bpermute_b32 v12, v168, v171
	s_mov_b64 s[4:5], 0x1100
	v_lshl_add_u64 v[4:5], v[4:5], 0, s[4:5]
	global_load_dwordx2 v[66:67], v[4:5], off
	global_load_dwordx2 v[68:69], v[4:5], off offset:16
	global_load_dwordx2 v[70:71], v[4:5], off offset:32
	global_load_dwordx2 v[72:73], v[4:5], off offset:48
	global_load_dwordx2 v[74:75], v[4:5], off offset:64
	global_load_dwordx2 v[76:77], v[4:5], off offset:80
	global_load_dwordx2 v[78:79], v[4:5], off offset:96
	global_load_dwordx2 v[80:81], v[4:5], off offset:112
	s_waitcnt lgkmcnt(0)
	v_add_f32_e32 v12, v171, v12
	v_div_scale_f32 v13, s[4:5], v12, v12, 1.0
	v_rcp_f32_e32 v14, v13
	v_div_scale_f32 v15, vcc, 1.0, v12, 1.0
	v_lshlrev_b64 v[2:3], 4, v[2:3]
	v_fma_f32 v48, -v13, v14, 1.0
	v_fmac_f32_e32 v14, v48, v14
	v_mul_f32_e32 v48, v15, v14
	v_fma_f32 v49, -v13, v48, v15
	v_fmac_f32_e32 v48, v49, v14
	v_fma_f32 v13, -v13, v48, v15
	v_and_b32_e32 v3, 0x1ffffff, v3
	v_and_b32_e32 v2, 0xffffffe0, v2
	v_div_fmas_f32 v13, v13, v14, v48
	v_lshl_add_u64 v[10:11], v[2:3], 0, s[8:9]
	v_div_fixup_f32 v12, v13, v12, 1.0
	v_lshlrev_b64 v[10:11], 7, v[10:11]
	v_lshl_add_u64 v[10:11], v[6:7], 0, v[10:11]
	v_lshl_add_u64 v[10:11], v[10:11], 0, v[0:1]
	v_lshl_add_u64 v[2:3], v[2:3], 0, s[28:29]
	v_lshlrev_b64 v[2:3], 7, v[2:3]
	v_lshl_add_u64 v[2:3], v[6:7], 0, v[2:3]
	v_lshl_add_u64 v[2:3], v[2:3], 0, v[0:1]
	s_add_i32 s92, s92, 1
	s_mov_b64 s[4:5], 0
	v_mul_f32_e32 v82, v32, v12
	v_mul_f32_e32 v83, v33, v12
	v_mul_f32_e32 v84, v34, v12
	v_mul_f32_e32 v85, v35, v12
	s_waitcnt vmcnt(7)
	v_lshlrev_b32_e32 v86, 16, v66
	v_and_b32_e32 v87, 0xffff0000, v66
	v_lshlrev_b32_e32 v88, 16, v67
	v_and_b32_e32 v89, 0xffff0000, v67
	v_mul_f32_e32 v82, v82, v86
	v_mul_f32_e32 v83, v83, v87
	v_mul_f32_e32 v84, v84, v88
	v_mul_f32_e32 v85, v85, v89
	v_cvt_pk_bf16_f32 v66, v82, v83
	v_cvt_pk_bf16_f32 v67, v84, v85
	global_store_dwordx2 v[10:11], v[66:67], off
	v_mul_f32_e32 v82, v36, v12
	v_mul_f32_e32 v83, v37, v12
	v_mul_f32_e32 v84, v38, v12
	v_mul_f32_e32 v85, v39, v12
	s_waitcnt vmcnt(7)
	v_lshlrev_b32_e32 v86, 16, v68
	v_and_b32_e32 v87, 0xffff0000, v68
	v_lshlrev_b32_e32 v88, 16, v69
	v_and_b32_e32 v89, 0xffff0000, v69
	v_mul_f32_e32 v82, v82, v86
	v_mul_f32_e32 v83, v83, v87
	v_mul_f32_e32 v84, v84, v88
	v_mul_f32_e32 v85, v85, v89
	v_cvt_pk_bf16_f32 v68, v82, v83
	v_cvt_pk_bf16_f32 v69, v84, v85
	global_store_dwordx2 v[10:11], v[68:69], off offset:16
	v_mul_f32_e32 v82, v40, v12
	v_mul_f32_e32 v83, v41, v12
	v_mul_f32_e32 v84, v42, v12
	v_mul_f32_e32 v85, v43, v12
	s_waitcnt vmcnt(7)
	v_lshlrev_b32_e32 v86, 16, v70
	v_and_b32_e32 v87, 0xffff0000, v70
	v_lshlrev_b32_e32 v88, 16, v71
	v_and_b32_e32 v89, 0xffff0000, v71
	v_mul_f32_e32 v82, v82, v86
	v_mul_f32_e32 v83, v83, v87
	v_mul_f32_e32 v84, v84, v88
	v_mul_f32_e32 v85, v85, v89
	v_cvt_pk_bf16_f32 v70, v82, v83
	v_cvt_pk_bf16_f32 v71, v84, v85
	global_store_dwordx2 v[10:11], v[70:71], off offset:32
	v_mul_f32_e32 v82, v44, v12
	v_mul_f32_e32 v83, v45, v12
	v_mul_f32_e32 v84, v46, v12
	v_mul_f32_e32 v85, v47, v12
	s_waitcnt vmcnt(7)
	v_lshlrev_b32_e32 v86, 16, v72
	v_and_b32_e32 v87, 0xffff0000, v72
	v_lshlrev_b32_e32 v88, 16, v73
	v_and_b32_e32 v89, 0xffff0000, v73
	v_mul_f32_e32 v82, v82, v86
	v_mul_f32_e32 v83, v83, v87
	v_mul_f32_e32 v84, v84, v88
	v_mul_f32_e32 v85, v85, v89
	v_cvt_pk_bf16_f32 v72, v82, v83
	v_cvt_pk_bf16_f32 v73, v84, v85
	global_store_dwordx2 v[10:11], v[72:73], off offset:48
	v_mul_f32_e32 v82, v16, v12
	v_mul_f32_e32 v83, v17, v12
	v_mul_f32_e32 v84, v18, v12
	v_mul_f32_e32 v85, v19, v12
	s_waitcnt vmcnt(7)
	v_lshlrev_b32_e32 v86, 16, v74
	v_and_b32_e32 v87, 0xffff0000, v74
	v_lshlrev_b32_e32 v88, 16, v75
	v_and_b32_e32 v89, 0xffff0000, v75
	v_mul_f32_e32 v82, v82, v86
	v_mul_f32_e32 v83, v83, v87
	v_mul_f32_e32 v84, v84, v88
	v_mul_f32_e32 v85, v85, v89
	v_cvt_pk_bf16_f32 v74, v82, v83
	v_cvt_pk_bf16_f32 v75, v84, v85
	global_store_dwordx2 v[2:3], v[74:75], off
	v_mul_f32_e32 v82, v20, v12
	v_mul_f32_e32 v83, v21, v12
	v_mul_f32_e32 v84, v22, v12
	v_mul_f32_e32 v85, v23, v12
	s_waitcnt vmcnt(7)
	v_lshlrev_b32_e32 v86, 16, v76
	v_and_b32_e32 v87, 0xffff0000, v76
	v_lshlrev_b32_e32 v88, 16, v77
	v_and_b32_e32 v89, 0xffff0000, v77
	v_mul_f32_e32 v82, v82, v86
	v_mul_f32_e32 v83, v83, v87
	v_mul_f32_e32 v84, v84, v88
	v_mul_f32_e32 v85, v85, v89
	v_cvt_pk_bf16_f32 v76, v82, v83
	v_cvt_pk_bf16_f32 v77, v84, v85
	global_store_dwordx2 v[2:3], v[76:77], off offset:16
	v_mul_f32_e32 v82, v24, v12
	v_mul_f32_e32 v83, v25, v12
	v_mul_f32_e32 v84, v26, v12
	v_mul_f32_e32 v85, v27, v12
	s_waitcnt vmcnt(7)
	v_lshlrev_b32_e32 v86, 16, v78
	v_and_b32_e32 v87, 0xffff0000, v78
	v_lshlrev_b32_e32 v88, 16, v79
	v_and_b32_e32 v89, 0xffff0000, v79
	v_mul_f32_e32 v82, v82, v86
	v_mul_f32_e32 v83, v83, v87
	v_mul_f32_e32 v84, v84, v88
	v_mul_f32_e32 v85, v85, v89
	v_cvt_pk_bf16_f32 v78, v82, v83
	v_cvt_pk_bf16_f32 v79, v84, v85
	global_store_dwordx2 v[2:3], v[78:79], off offset:32
	v_mul_f32_e32 v82, v28, v12
	v_mul_f32_e32 v83, v29, v12
	v_mul_f32_e32 v84, v30, v12
	v_mul_f32_e32 v85, v31, v12
	s_waitcnt vmcnt(7)
	v_lshlrev_b32_e32 v86, 16, v80
	v_and_b32_e32 v87, 0xffff0000, v80
	v_lshlrev_b32_e32 v88, 16, v81
	v_and_b32_e32 v89, 0xffff0000, v81
	v_mul_f32_e32 v82, v82, v86
	v_mul_f32_e32 v83, v83, v87
	v_mul_f32_e32 v84, v84, v88
	v_mul_f32_e32 v85, v85, v89
	v_cvt_pk_bf16_f32 v80, v82, v83
	v_cvt_pk_bf16_f32 v81, v84, v85
	global_store_dwordx2 v[2:3], v[80:81], off offset:48
	s_barrier

.LBB0_185:
	s_or_b64 exec, exec, s[84:85]
	v_ashrrev_i32_e32 v6, 1, v83
	v_readlane_b32 s31, v242, 8
	v_and_b32_e32 v0, 0xffffffe0, v6
	s_add_u32 s34, s28, s31
	v_readlane_b32 s31, v242, 14
	v_add_u32_e32 v0, s70, v0
	v_and_b32_e32 v7, 31, v83
	s_addc_u32 s35, s29, s31
	v_or_b32_e32 v108, v0, v7
	v_mov_b64_e32 v[80:81], s[34:35]
	v_bfe_u32 v115, v83, 5, 1
	v_mad_i64_i32 v[2:3], s[82:83], v108, s38, v[80:81]
	v_lshl_add_u64 v[2:3], v[2:3], 0, s[10:11]
	v_lshlrev_b32_e32 v106, 4, v115
	v_mov_b32_e32 v107, v1
	v_lshl_add_u64 v[2:3], v[2:3], 0, v[106:107]
	s_mov_b64 s[82:83], 0x1400
	s_movk_i32 s36, 0x1000
	v_lshl_add_u64 v[4:5], v[2:3], 0, s[82:83]
	v_add_co_u32_e32 v2, vcc, s36, v2
	s_movk_i32 s31, 0xffe0
	s_nop 0
	v_addc_co_u32_e32 v3, vcc, 0, v3, vcc
	global_load_dwordx4 v[74:77], v[2:3], off offset:1024
	global_load_dwordx4 v[70:73], v[4:5], off offset:32
	global_load_dwordx4 v[66:69], v[4:5], off offset:64
	v_bfi_b32 v2, s31, v6, v83
	v_add_u32_e32 v3, 1, v2
	v_sub_u32_e32 v2, 0x80, v2
	v_cvt_f32_i32_e32 v3, v3
	v_cvt_f32_i32_e32 v2, v2
	s_movk_i32 s37, 0x90
	v_mad_u32_u24 v107, v7, s37, v106
	s_waitcnt vmcnt(4)
	v_mul_f32_e32 v3, v112, v3
	s_waitcnt vmcnt(3)
	v_mul_f32_e32 v2, v113, v2
	s_waitcnt lgkmcnt(0)
	s_barrier
	v_exp_f32_e32 v82, v3
	v_exp_f32_e32 v96, v2
	ds_read_b128 v[2:5], v107 offset:22528
	ds_read_b128 v[18:21], v107 offset:22560
	ds_read_b128 v[34:37], v107 offset:36384
	ds_read_b128 v[50:53], v107 offset:40992
	ds_read_b128 v[92:95], v107 offset:45600
	v_ashrrev_i32_e32 v104, 3, v83
	s_mov_b32 s99, s11
	s_add_u32 s34, s34, s30
	s_mov_b32 s40, 0x3c000
	s_addc_u32 s35, s35, 0
	s_add_u32 s34, s34, 0x1800
	s_addc_u32 s35, s35, 0
	s_movk_i32 s39, 0xd0
	v_and_b32_e32 v78, 24, v78
	v_mul_i32_i24_e32 v116, -4, v115
	v_add_u32_e32 v118, -8, v108
	v_subrev_u32_e32 v117, 24, v108
	v_ashrrev_i32_e32 v109, 31, v108
	s_mov_b32 s31, s11
	v_lshlrev_b32_e32 v0, 3, v115
	s_add_u32 s6, s6, s0
	s_addc_u32 s7, s7, s1
	s_add_i32 s71, s71, 1
	s_waitcnt vmcnt(2) lgkmcnt(4)
	v_mfma_f32_32x32x16_bf16 v[2:17], v[2:5], v[74:77], 0
	s_waitcnt vmcnt(1) lgkmcnt(3)
	v_mfma_f32_32x32x16_bf16 v[2:17], v[18:21], v[70:73], v[2:17]
	ds_read_b128 v[18:21], v107 offset:22592
	s_waitcnt vmcnt(0) lgkmcnt(0)
	v_mfma_f32_32x32x16_bf16 v[2:17], v[18:21], v[66:69], v[2:17]
	ds_read_b128 v[18:21], v107 offset:36352
	s_waitcnt lgkmcnt(0)
	v_mfma_f32_32x32x16_bf16 v[18:33], v[18:21], v[74:77], 0
	v_mfma_f32_32x32x16_bf16 v[18:33], v[34:37], v[70:73], v[18:33]
	ds_read_b128 v[34:37], v107 offset:36416
	s_waitcnt lgkmcnt(0)
	v_mfma_f32_32x32x16_bf16 v[18:33], v[34:37], v[66:69], v[18:33]
	s_nop 11
	v_pk_mul_f32 v[20:21], v[96:97], v[20:21] op_sel_hi:[0,1]
	v_pk_mul_f32 v[18:19], v[96:97], v[18:19] op_sel_hi:[0,1]
	v_pk_fma_f32 v[36:37], v[82:83], v[4:5], v[20:21] op_sel_hi:[0,1,1]
	v_pk_fma_f32 v[34:35], v[82:83], v[2:3], v[18:19] op_sel_hi:[0,1,1]
	ds_read_b128 v[2:5], v107 offset:27136
	v_pk_mul_f32 v[22:23], v[96:97], v[22:23] op_sel_hi:[0,1]
	v_pk_mul_f32 v[24:25], v[96:97], v[24:25] op_sel_hi:[0,1]
	v_pk_mul_f32 v[26:27], v[96:97], v[26:27] op_sel_hi:[0,1]
	v_pk_mul_f32 v[28:29], v[96:97], v[28:29] op_sel_hi:[0,1]
	v_pk_mul_f32 v[30:31], v[96:97], v[30:31] op_sel_hi:[0,1]
	v_pk_mul_f32 v[32:33], v[96:97], v[32:33] op_sel_hi:[0,1]
	ds_read_b128 v[18:21], v107 offset:27168
	v_pk_fma_f32 v[48:49], v[82:83], v[16:17], v[32:33] op_sel_hi:[0,1,1]
	v_pk_fma_f32 v[46:47], v[82:83], v[14:15], v[30:31] op_sel_hi:[0,1,1]
	v_pk_fma_f32 v[44:45], v[82:83], v[12:13], v[28:29] op_sel_hi:[0,1,1]
	v_pk_fma_f32 v[42:43], v[82:83], v[10:11], v[26:27] op_sel_hi:[0,1,1]
	v_pk_fma_f32 v[40:41], v[82:83], v[8:9], v[24:25] op_sel_hi:[0,1,1]
	v_pk_fma_f32 v[38:39], v[82:83], v[6:7], v[22:23] op_sel_hi:[0,1,1]
	s_waitcnt lgkmcnt(1)
	v_mfma_f32_32x32x16_bf16 v[2:17], v[2:5], v[74:77], 0
	s_waitcnt lgkmcnt(0)
	v_mfma_f32_32x32x16_bf16 v[2:17], v[18:21], v[70:73], v[2:17]
	ds_read_b128 v[18:21], v107 offset:27200
	s_waitcnt lgkmcnt(0)
	v_mfma_f32_32x32x16_bf16 v[2:17], v[18:21], v[66:69], v[2:17]
	ds_read_b128 v[18:21], v107 offset:40960
	s_waitcnt lgkmcnt(0)
	v_mfma_f32_32x32x16_bf16 v[18:33], v[18:21], v[74:77], 0
	v_mfma_f32_32x32x16_bf16 v[18:33], v[50:53], v[70:73], v[18:33]
	ds_read_b128 v[50:53], v107 offset:41024
	s_waitcnt lgkmcnt(0)
	v_mfma_f32_32x32x16_bf16 v[18:33], v[50:53], v[66:69], v[18:33]
	ds_read_b128 v[50:53], v107 offset:31776
	s_nop 10
	v_pk_mul_f32 v[20:21], v[96:97], v[20:21] op_sel_hi:[0,1]
	v_pk_mul_f32 v[18:19], v[96:97], v[18:19] op_sel_hi:[0,1]
	v_pk_fma_f32 v[20:21], v[82:83], v[4:5], v[20:21] op_sel_hi:[0,1,1]
	v_pk_fma_f32 v[18:19], v[82:83], v[2:3], v[18:19] op_sel_hi:[0,1,1]
	ds_read_b128 v[2:5], v107 offset:31744
	v_pk_mul_f32 v[22:23], v[96:97], v[22:23] op_sel_hi:[0,1]
	v_pk_mul_f32 v[24:25], v[96:97], v[24:25] op_sel_hi:[0,1]
	v_pk_mul_f32 v[26:27], v[96:97], v[26:27] op_sel_hi:[0,1]
	v_pk_mul_f32 v[28:29], v[96:97], v[28:29] op_sel_hi:[0,1]
	v_pk_mul_f32 v[30:31], v[96:97], v[30:31] op_sel_hi:[0,1]
	v_pk_mul_f32 v[32:33], v[96:97], v[32:33] op_sel_hi:[0,1]
	v_pk_fma_f32 v[32:33], v[82:83], v[16:17], v[32:33] op_sel_hi:[0,1,1]
	v_pk_fma_f32 v[30:31], v[82:83], v[14:15], v[30:31] op_sel_hi:[0,1,1]
	v_pk_fma_f32 v[28:29], v[82:83], v[12:13], v[28:29] op_sel_hi:[0,1,1]
	v_pk_fma_f32 v[26:27], v[82:83], v[10:11], v[26:27] op_sel_hi:[0,1,1]
	v_pk_fma_f32 v[24:25], v[82:83], v[8:9], v[24:25] op_sel_hi:[0,1,1]
	v_pk_fma_f32 v[22:23], v[82:83], v[6:7], v[22:23] op_sel_hi:[0,1,1]
	s_waitcnt lgkmcnt(0)
	v_mfma_f32_32x32x16_bf16 v[2:17], v[2:5], v[74:77], 0
	v_mfma_f32_32x32x16_bf16 v[2:17], v[50:53], v[70:73], v[2:17]
	ds_read_b128 v[50:53], v107 offset:31808
	s_waitcnt lgkmcnt(0)
	v_mfma_f32_32x32x16_bf16 v[2:17], v[50:53], v[66:69], v[2:17]
	ds_read_b128 v[50:53], v107 offset:45568
	s_waitcnt lgkmcnt(0)
	v_mfma_f32_32x32x16_bf16 v[50:65], v[50:53], v[74:77], 0
	v_mfma_f32_32x32x16_bf16 v[50:65], v[92:95], v[70:73], v[50:65]
	ds_read_b128 v[92:95], v107 offset:45632
	s_waitcnt lgkmcnt(0)
	v_mfma_f32_32x32x16_bf16 v[50:65], v[92:95], v[66:69], v[50:65]
	s_nop 11
	v_pk_mul_f32 v[50:51], v[96:97], v[50:51] op_sel_hi:[0,1]
	v_pk_fma_f32 v[2:3], v[82:83], v[2:3], v[50:51] op_sel_hi:[0,1,1]
	v_ashrrev_i32_e32 v50, 1, v84
	v_add_u32_e32 v91, v50, v85
	v_mul_lo_u32 v50, v91, 12
	v_pk_mul_f32 v[52:53], v[96:97], v[52:53] op_sel_hi:[0,1]
	v_pk_mul_f32 v[54:55], v[96:97], v[54:55] op_sel_hi:[0,1]
	v_pk_mul_f32 v[56:57], v[96:97], v[56:57] op_sel_hi:[0,1]
	v_pk_mul_f32 v[58:59], v[96:97], v[58:59] op_sel_hi:[0,1]
	v_pk_mul_f32 v[60:61], v[96:97], v[60:61] op_sel_hi:[0,1]
	v_pk_mul_f32 v[62:63], v[96:97], v[62:63] op_sel_hi:[0,1]
	v_pk_mul_f32 v[64:65], v[96:97], v[64:65] op_sel_hi:[0,1]
	v_sub_u32_e32 v84, v83, v50
	v_ashrrev_i32_e32 v50, 1, v86
	v_pk_fma_f32 v[16:17], v[82:83], v[16:17], v[64:65] op_sel_hi:[0,1,1]
	v_pk_fma_f32 v[14:15], v[82:83], v[14:15], v[62:63] op_sel_hi:[0,1,1]
	v_pk_fma_f32 v[12:13], v[82:83], v[12:13], v[60:61] op_sel_hi:[0,1,1]
	v_pk_fma_f32 v[10:11], v[82:83], v[10:11], v[58:59] op_sel_hi:[0,1,1]
	v_pk_fma_f32 v[8:9], v[82:83], v[8:9], v[56:57] op_sel_hi:[0,1,1]
	v_pk_fma_f32 v[6:7], v[82:83], v[6:7], v[54:55] op_sel_hi:[0,1,1]
	v_pk_fma_f32 v[4:5], v[82:83], v[4:5], v[52:53] op_sel_hi:[0,1,1]
	v_add_u32_e32 v82, v50, v87
	v_mul_lo_u32 v50, v82, 12
	v_sub_u32_e32 v79, v79, v50
	v_ashrrev_i32_e32 v50, 1, v89
	v_add_u32_e32 v85, v50, v90
	v_mul_lo_u32 v50, v85, 12
	v_sub_u32_e32 v90, v88, v50
	v_mad_i64_i32 v[50:51], s[82:83], v104, s38, v[80:81]
	v_lshlrev_b32_e32 v52, 4, v83
	v_lshl_add_u64 v[50:51], v[50:51], 0, s[10:11]
	v_and_b32_e32 v64, 0x70, v52
	v_mov_b32_e32 v65, v1
	v_lshl_add_u64 v[50:51], v[50:51], 0, v[64:65]
	s_mov_b64 s[82:83], 0x1600
	v_lshl_add_u64 v[62:63], v[50:51], 0, s[82:83]
	v_lshl_add_u64 v[54:55], v[62:63], 0, s[98:99]
	global_load_dwordx4 v[50:53], v[54:55], off
	v_add_co_u32_e32 v54, vcc, s40, v54
	v_lshlrev_b32_e32 v92, 3, v79
	s_nop 0
	v_addc_co_u32_e32 v55, vcc, 0, v55, vcc
	global_load_dwordx4 v[54:57], v[54:55], off
	v_mov_b64_e32 v[86:87], s[34:35]
	v_add_u32_e32 v65, s70, v82
	v_ashrrev_i32_e32 v93, 31, v92
	v_lshlrev_b32_e32 v60, 3, v84
	v_mad_i64_i32 v[80:81], s[34:35], v65, s38, v[86:87]
	v_lshlrev_b64 v[100:101], 1, v[92:93]
	v_lshlrev_b32_e32 v96, 3, v90
	v_add_u32_e32 v58, s70, v91
	v_ashrrev_i32_e32 v61, 31, v60
	v_lshl_add_u64 v[80:81], v[80:81], 0, v[100:101]
	v_add_u32_e32 v65, s70, v85
	v_ashrrev_i32_e32 v97, 31, v96
	v_mad_i64_i32 v[58:59], s[34:35], v58, s38, v[86:87]
	v_lshlrev_b64 v[88:89], 1, v[60:61]
	global_load_dwordx4 v[92:95], v[80:81], off
	v_mad_i64_i32 v[80:81], s[34:35], v65, s38, v[86:87]
	v_lshlrev_b64 v[102:103], 1, v[96:97]
	v_lshl_add_u64 v[58:59], v[58:59], 0, v[88:89]
	v_lshl_add_u64 v[80:81], v[80:81], 0, v[102:103]
	global_load_dwordx4 v[58:61], v[58:59], off
	v_lshrrev_b32_e32 v65, 3, v83
	global_load_dwordx4 v[96:99], v[80:81], off
	v_bfe_u32 v80, v83, 2, 2
	v_and_or_b32 v65, v65, 4, v80
	v_mad_u64_u32 v[110:111], s[34:35], v104, s37, v[64:65]
	s_barrier
	s_waitcnt vmcnt(4)
	ds_write_b128 v110, v[50:53]
	s_waitcnt vmcnt(3)
	ds_write_b128 v110, v[54:57] offset:4608
	v_mul_lo_u32 v50, v91, s39
	v_lshl_add_u32 v119, v84, 4, v50
	v_mul_lo_u32 v50, v82, s39
	v_lshl_add_u32 v120, v79, 4, v50
	v_mul_lo_u32 v50, v85, s39
	v_lshl_add_u32 v121, v90, 4, v50
	v_add_u32_e32 v50, s68, v85
	v_and_b32_e32 v80, 16, v83
	v_mad_i64_i32 v[50:51], s[34:35], v50, s38, v[86:87]
	v_lshl_or_b32 v78, v80, 1, v78
	v_lshl_add_u64 v[50:51], v[50:51], 0, v[102:103]
	v_mad_u32_u24 v114, v65, s39, v78
	v_add_u32_e32 v111, -16, v108
	s_waitcnt vmcnt(1)
	ds_write_b128 v119, v[58:61] offset:9216
	ds_write_b128 v120, v[92:95] offset:9216
	s_waitcnt vmcnt(0)
	ds_write_b128 v121, v[96:99] offset:9216
	s_waitcnt lgkmcnt(0)
	s_barrier
	global_load_dwordx4 v[78:81], v[50:51], off
	v_add_u32_e32 v50, s68, v82
	v_mad_i64_i32 v[50:51], s[34:35], v50, s38, v[86:87]
	v_lshl_add_u64 v[50:51], v[50:51], 0, v[100:101]
	global_load_dwordx4 v[82:85], v[50:51], off
	v_add_u32_e32 v50, s68, v91
	v_mad_i64_i32 v[50:51], s[34:35], v50, s38, v[86:87]
	v_readlane_b32 s34, v242, 10
	v_lshl_add_u64 v[50:51], v[50:51], 0, v[88:89]
	v_readlane_b32 s35, v242, 11
	global_load_dwordx4 v[86:89], v[50:51], off
	s_nop 0
	v_lshl_add_u64 v[50:51], v[62:63], 0, s[34:35]
	v_add_co_u32_e32 v52, vcc, s40, v50
	v_readlane_b32 s34, v242, 26
	s_nop 0
	v_addc_co_u32_e32 v53, vcc, 0, v51, vcc
	global_load_dwordx4 v[90:93], v[52:53], off
	global_load_dwordx4 v[94:97], v[50:51], off
	ds_read_b128 v[50:53], v107
	ds_read_b128 v[98:101], v107 offset:32
	s_waitcnt lgkmcnt(1)
	v_mfma_f32_32x32x16_bf16 v[50:65], v[50:53], v[74:77], 0
	ds_read_b128 v[122:125], v107 offset:4640
	s_waitcnt lgkmcnt(1)
	v_mfma_f32_32x32x16_bf16 v[50:65], v[98:101], v[70:73], v[50:65]
	ds_read_b128 v[98:101], v107 offset:64
	s_waitcnt lgkmcnt(0)
	v_mfma_f32_32x32x16_bf16 v[50:65], v[98:101], v[66:69], v[50:65]
	v_subrev_u32_e32 v100, s70, v116
	v_add_u32_e32 v98, v108, v100
	v_cvt_f32_i32_e32 v99, v98
	v_cmp_gt_i32_e32 vcc, 0, v98
	v_mad_i32_i24 v101, v115, -4, s34
	v_readlane_b32 s34, v242, 27
	v_cndmask_b32_e64 v98, v112, -v113, vcc
	v_mul_f32_e32 v98, v98, v99
	v_add_u32_e32 v99, v108, v101
	v_cvt_f32_i32_e32 v102, v99
	v_cmp_gt_i32_e32 vcc, 0, v99
	v_exp_f32_e32 v98, v98
	s_nop 0
	v_cndmask_b32_e64 v99, v112, -v113, vcc
	v_mul_f32_e32 v99, v99, v102
	v_exp_f32_e32 v99, v99
	v_subrev_u32_e32 v102, s34, v116
	v_readlane_b32 s34, v242, 28
	v_pk_mul_f32 v[50:51], v[98:99], v[50:51]
	v_add_u32_e32 v98, v108, v102
	v_cvt_f32_i32_e32 v99, v98
	v_cmp_gt_i32_e32 vcc, 0, v98
	v_subrev_u32_e32 v103, s34, v116
	v_readlane_b32 s34, v242, 29
	v_cndmask_b32_e64 v98, v112, -v113, vcc
	v_mul_f32_e32 v98, v98, v99
	v_add_u32_e32 v99, v108, v103
	v_cvt_f32_i32_e32 v104, v99
	v_cmp_gt_i32_e32 vcc, 0, v99
	v_exp_f32_e32 v98, v98
	v_subrev_u32_e32 v126, s34, v116
	v_cndmask_b32_e64 v99, v112, -v113, vcc
	v_mul_f32_e32 v99, v99, v104
	v_exp_f32_e32 v99, v99
	v_readlane_b32 s34, v242, 30
	v_pk_mul_f32 v[52:53], v[98:99], v[52:53]
	v_add_u32_e32 v98, v118, v100
	v_cvt_f32_i32_e32 v99, v98
	v_cmp_gt_i32_e32 vcc, 0, v98
	v_subrev_u32_e32 v127, s34, v116
	v_readlane_b32 s34, v242, 31
	v_cndmask_b32_e64 v98, v112, -v113, vcc
	v_mul_f32_e32 v98, v98, v99
	v_add_u32_e32 v99, v118, v101
	v_cvt_f32_i32_e32 v104, v99
	v_cmp_gt_i32_e32 vcc, 0, v99
	v_exp_f32_e32 v98, v98
	v_subrev_u32_e32 v128, s34, v116
	v_cndmask_b32_e64 v99, v112, -v113, vcc
	v_mul_f32_e32 v99, v99, v104
	v_exp_f32_e32 v99, v99
	v_readlane_b32 s34, v242, 32
	v_pk_mul_f32 v[54:55], v[98:99], v[54:55]
	v_add_u32_e32 v98, v118, v102
	v_cvt_f32_i32_e32 v99, v98
	v_cmp_gt_i32_e32 vcc, 0, v98
	v_subrev_u32_e32 v129, s34, v116
	v_readlane_b32 s34, v242, 35
	v_cndmask_b32_e64 v98, v112, -v113, vcc
	v_mul_f32_e32 v98, v98, v99
	v_add_u32_e32 v99, v118, v103
	v_cvt_f32_i32_e32 v104, v99
	v_cmp_gt_i32_e32 vcc, 0, v99
	v_exp_f32_e32 v98, v98
	s_nop 0
	v_cndmask_b32_e64 v99, v112, -v113, vcc
	v_mul_f32_e32 v99, v99, v104
	v_exp_f32_e32 v99, v99
	s_nop 0
	v_pk_mul_f32 v[56:57], v[98:99], v[56:57]
	v_add_u32_e32 v98, v111, v100
	v_cvt_f32_i32_e32 v99, v98
	v_cmp_gt_i32_e32 vcc, 0, v98
	v_cvt_pk_bf16_f32 v105, v56, v57
	s_nop 0
	v_cndmask_b32_e64 v98, v112, -v113, vcc
	v_mul_f32_e32 v98, v98, v99
	v_add_u32_e32 v99, v111, v101
	v_cvt_f32_i32_e32 v104, v99
	v_cmp_gt_i32_e32 vcc, 0, v99
	v_exp_f32_e32 v98, v98
	s_nop 0
	v_cndmask_b32_e64 v99, v112, -v113, vcc
	v_mul_f32_e32 v99, v99, v104
	v_exp_f32_e32 v99, v99
	s_nop 0
	v_pk_mul_f32 v[58:59], v[98:99], v[58:59]
	v_add_u32_e32 v98, v111, v102
	v_cvt_f32_i32_e32 v99, v98
	v_cmp_gt_i32_e32 vcc, 0, v98
	s_nop 1
	v_cndmask_b32_e64 v98, v112, -v113, vcc
	v_mul_f32_e32 v98, v98, v99
	v_add_u32_e32 v99, v111, v103
	v_cvt_f32_i32_e32 v104, v99
	v_cmp_gt_i32_e32 vcc, 0, v99
	v_exp_f32_e32 v98, v98
	s_nop 0
	v_cndmask_b32_e64 v99, v112, -v113, vcc
	v_mul_f32_e32 v99, v99, v104
	v_exp_f32_e32 v99, v99
	v_cvt_pk_bf16_f32 v104, v54, v55
	v_pk_mul_f32 v[60:61], v[98:99], v[60:61]
	v_add_u32_e32 v98, v117, v100
	v_cvt_f32_i32_e32 v99, v98
	v_cmp_gt_i32_e32 vcc, 0, v98
	s_nop 1
	v_cndmask_b32_e64 v98, v112, -v113, vcc
	v_mul_f32_e32 v98, v98, v99
	v_add_u32_e32 v99, v117, v101
	v_cvt_f32_i32_e32 v100, v99
	v_cmp_gt_i32_e32 vcc, 0, v99
	v_exp_f32_e32 v98, v98
	s_nop 0
	v_cndmask_b32_e64 v99, v112, -v113, vcc
	v_mul_f32_e32 v99, v99, v100
	v_exp_f32_e32 v99, v99
	s_nop 0
	v_pk_mul_f32 v[62:63], v[98:99], v[62:63]
	v_add_u32_e32 v98, v117, v102
	v_cvt_f32_i32_e32 v99, v98
	v_cmp_gt_i32_e32 vcc, 0, v98
	v_cvt_pk_bf16_f32 v102, v50, v51
	s_nop 0
	v_cndmask_b32_e64 v98, v112, -v113, vcc
	v_mul_f32_e32 v98, v98, v99
	v_add_u32_e32 v99, v117, v103
	v_cvt_f32_i32_e32 v100, v99
	v_cvt_pk_bf16_f32 v103, v52, v53
	ds_read_b128 v[50:53], v107 offset:4608
	v_cmp_gt_i32_e32 vcc, 0, v99
	v_exp_f32_e32 v98, v98
	s_nop 0
	v_cndmask_b32_e64 v99, v112, -v113, vcc
	v_mul_f32_e32 v99, v99, v100
	v_exp_f32_e32 v99, v99
	v_cvt_pk_bf16_f32 v100, v62, v63
	v_pk_mul_f32 v[64:65], v[98:99], v[64:65]
	v_cvt_pk_bf16_f32 v98, v58, v59
	v_cvt_pk_bf16_f32 v99, v60, v61
	v_cvt_pk_bf16_f32 v101, v64, v65
	s_waitcnt lgkmcnt(0)
	v_mfma_f32_32x32x16_bf16 v[50:65], v[50:53], v[74:77], 0
	v_mfma_f32_32x32x16_bf16 v[50:65], v[122:125], v[70:73], v[50:65]
	ds_read_b128 v[122:125], v107 offset:4672
	s_waitcnt lgkmcnt(0)
	v_mfma_f32_32x32x16_bf16 v[50:65], v[122:125], v[66:69], v[50:65]
	v_add_u32_e32 v122, v108, v126
	v_cvt_f32_i32_e32 v123, v122
	v_cmp_gt_i32_e32 vcc, 0, v122
	s_nop 1
	v_cndmask_b32_e64 v122, v112, -v113, vcc
	v_mul_f32_e32 v122, v122, v123
	v_add_u32_e32 v123, v108, v127
	v_cvt_f32_i32_e32 v124, v123
	v_cmp_gt_i32_e32 vcc, 0, v123
	v_exp_f32_e32 v122, v122
	s_nop 0
	v_cndmask_b32_e64 v123, v112, -v113, vcc
	v_mul_f32_e32 v123, v123, v124
	v_exp_f32_e32 v123, v123
	s_nop 0
	v_pk_mul_f32 v[50:51], v[122:123], v[50:51]
	v_add_u32_e32 v122, v108, v128
	v_cvt_f32_i32_e32 v123, v122
	v_cmp_gt_i32_e32 vcc, 0, v122
	s_nop 1
	v_cndmask_b32_e64 v122, v112, -v113, vcc
	v_mul_f32_e32 v122, v122, v123
	v_add_u32_e32 v123, v108, v129
	v_cvt_f32_i32_e32 v124, v123
	v_cmp_gt_i32_e32 vcc, 0, v123
	v_exp_f32_e32 v122, v122
	s_nop 0
	v_cndmask_b32_e64 v123, v112, -v113, vcc
	v_mul_f32_e32 v123, v123, v124
	v_exp_f32_e32 v123, v123
	s_nop 0
	v_pk_mul_f32 v[52:53], v[122:123], v[52:53]
	v_add_u32_e32 v122, v118, v126
	v_cvt_f32_i32_e32 v123, v122
	v_cmp_gt_i32_e32 vcc, 0, v122
	s_nop 1
	v_cndmask_b32_e64 v122, v112, -v113, vcc
	v_mul_f32_e32 v122, v122, v123
	v_add_u32_e32 v123, v118, v127
	v_cvt_f32_i32_e32 v124, v123
	v_cmp_gt_i32_e32 vcc, 0, v123
	v_exp_f32_e32 v122, v122
	s_nop 0
	v_cndmask_b32_e64 v123, v112, -v113, vcc
	v_mul_f32_e32 v123, v123, v124
	v_exp_f32_e32 v123, v123
	s_nop 0
	v_pk_mul_f32 v[122:123], v[122:123], v[54:55]
	v_add_u32_e32 v54, v118, v128
	v_cvt_f32_i32_e32 v55, v54
	v_cmp_gt_i32_e32 vcc, 0, v54
	s_nop 1
	v_cndmask_b32_e64 v54, v112, -v113, vcc
	v_mul_f32_e32 v54, v54, v55
	v_add_u32_e32 v55, v118, v129
	v_cvt_f32_i32_e32 v124, v55
	v_cmp_gt_i32_e32 vcc, 0, v55
	v_exp_f32_e32 v54, v54
	s_nop 0
	v_cndmask_b32_e64 v55, v112, -v113, vcc
	v_mul_f32_e32 v55, v55, v124
	v_exp_f32_e32 v55, v55
	s_nop 0
	v_pk_mul_f32 v[124:125], v[54:55], v[56:57]
	v_add_u32_e32 v54, v111, v126
	v_cvt_f32_i32_e32 v55, v54
	v_cmp_gt_i32_e32 vcc, 0, v54
	v_cvt_pk_bf16_f32 v57, v124, v125
	s_nop 0
	v_cndmask_b32_e64 v54, v112, -v113, vcc
	v_mul_f32_e32 v54, v54, v55
	v_add_u32_e32 v55, v111, v127
	v_cvt_f32_i32_e32 v56, v55
	v_cmp_gt_i32_e32 vcc, 0, v55
	v_exp_f32_e32 v54, v54
	s_nop 0
	v_cndmask_b32_e64 v55, v112, -v113, vcc
	v_mul_f32_e32 v55, v55, v56
	v_exp_f32_e32 v55, v55
	s_nop 0
	v_pk_mul_f32 v[58:59], v[54:55], v[58:59]
	v_add_u32_e32 v54, v111, v128
	v_cvt_f32_i32_e32 v55, v54
	v_cmp_gt_i32_e32 vcc, 0, v54
	s_nop 1
	v_cndmask_b32_e64 v54, v112, -v113, vcc
	v_mul_f32_e32 v54, v54, v55
	v_add_u32_e32 v55, v111, v129
	v_cvt_f32_i32_e32 v56, v55
	v_cmp_gt_i32_e32 vcc, 0, v55
	v_exp_f32_e32 v54, v54
	s_nop 0
	v_cndmask_b32_e64 v55, v112, -v113, vcc
	v_mul_f32_e32 v55, v55, v56
	v_exp_f32_e32 v55, v55
	s_nop 0
	v_pk_mul_f32 v[60:61], v[54:55], v[60:61]
	v_add_u32_e32 v54, v117, v126
	v_cvt_f32_i32_e32 v55, v54
	v_cmp_gt_i32_e32 vcc, 0, v54
	s_nop 1
	v_cndmask_b32_e64 v54, v112, -v113, vcc
	v_mul_f32_e32 v54, v54, v55
	v_add_u32_e32 v55, v117, v127
	v_cvt_f32_i32_e32 v56, v55
	v_cmp_gt_i32_e32 vcc, 0, v55
	v_exp_f32_e32 v54, v54
	s_nop 0
	v_cndmask_b32_e64 v55, v112, -v113, vcc
	v_mul_f32_e32 v55, v55, v56
	v_exp_f32_e32 v55, v55
	s_nop 0
	v_pk_mul_f32 v[62:63], v[54:55], v[62:63]
	v_add_u32_e32 v54, v117, v128
	v_cvt_f32_i32_e32 v55, v54
	v_cmp_gt_i32_e32 vcc, 0, v54
	s_nop 1
	v_cndmask_b32_e64 v54, v112, -v113, vcc
	v_mul_f32_e32 v54, v54, v55
	v_add_u32_e32 v55, v117, v129
	v_cvt_f32_i32_e32 v56, v55
	v_cmp_gt_i32_e32 vcc, 0, v55
	v_exp_f32_e32 v54, v54
	s_nop 0
	v_cndmask_b32_e64 v55, v112, -v113, vcc
	v_mul_f32_e32 v55, v55, v56
	v_exp_f32_e32 v55, v55
	v_cvt_pk_bf16_f32 v56, v122, v123
	v_pk_mul_f32 v[64:65], v[54:55], v[64:65]
	v_cvt_pk_bf16_f32 v54, v50, v51
	v_cvt_pk_bf16_f32 v50, v58, v59
	v_cvt_pk_bf16_f32 v51, v60, v61
	ds_read_b64_tr_b16 v[58:59], v114 offset:9216
	ds_read_b64_tr_b16 v[60:61], v114 offset:10880
	ds_read_b64_tr_b16 v[136:137], v114 offset:9280
	ds_read_b64_tr_b16 v[138:139], v114 offset:10944
	s_waitcnt lgkmcnt(2)
	v_mfma_f32_32x32x16_bf16 v[34:49], v[58:61], v[102:105], v[34:49]
	ds_read_b64_tr_b16 v[58:59], v114 offset:9344
	ds_read_b64_tr_b16 v[60:61], v114 offset:11008
	v_cvt_pk_bf16_f32 v55, v52, v53
	v_cvt_pk_bf16_f32 v52, v62, v63
	v_cvt_pk_bf16_f32 v53, v64, v65
	s_waitcnt lgkmcnt(2)
	v_mfma_f32_32x32x16_bf16 v[18:33], v[136:139], v[102:105], v[18:33]
	ds_read_b64_tr_b16 v[136:137], v114 offset:12544
	ds_read_b64_tr_b16 v[138:139], v114 offset:14208
	s_waitcnt lgkmcnt(2)
	v_mfma_f32_32x32x16_bf16 v[2:17], v[58:61], v[102:105], v[2:17]
	ds_read_b64_tr_b16 v[58:59], v114 offset:12608
	ds_read_b64_tr_b16 v[60:61], v114 offset:14272
	s_waitcnt lgkmcnt(2)
	v_mfma_f32_32x32x16_bf16 v[34:49], v[136:139], v[98:101], v[34:49]
	ds_read_b64_tr_b16 v[136:137], v114 offset:12672
	ds_read_b64_tr_b16 v[138:139], v114 offset:14336
	s_waitcnt lgkmcnt(2)
	v_mfma_f32_32x32x16_bf16 v[18:33], v[58:61], v[98:101], v[18:33]
	ds_read_b64_tr_b16 v[58:59], v114 offset:15872
	ds_read_b64_tr_b16 v[60:61], v114 offset:17536
	s_waitcnt lgkmcnt(2)
	v_mfma_f32_32x32x16_bf16 v[2:17], v[136:139], v[98:101], v[2:17]
	ds_read_b64_tr_b16 v[136:137], v114 offset:15936
	ds_read_b64_tr_b16 v[138:139], v114 offset:17600
	s_waitcnt lgkmcnt(2)
	v_mfma_f32_32x32x16_bf16 v[34:49], v[58:61], v[54:57], v[34:49]
	ds_read_b64_tr_b16 v[58:59], v114 offset:16000
	ds_read_b64_tr_b16 v[60:61], v114 offset:17664
	s_waitcnt lgkmcnt(2)
	v_mfma_f32_32x32x16_bf16 v[18:33], v[136:139], v[54:57], v[18:33]
	ds_read_b64_tr_b16 v[136:137], v114 offset:19200
	ds_read_b64_tr_b16 v[138:139], v114 offset:20864
	s_waitcnt lgkmcnt(2)
	v_mfma_f32_32x32x16_bf16 v[2:17], v[58:61], v[54:57], v[2:17]
	ds_read_b64_tr_b16 v[54:55], v114 offset:19264
	ds_read_b64_tr_b16 v[56:57], v114 offset:20928
	s_waitcnt lgkmcnt(2)
	v_mfma_f32_32x32x16_bf16 v[34:49], v[136:139], v[50:53], v[34:49]
	s_waitcnt lgkmcnt(0)
	v_mfma_f32_32x32x16_bf16 v[18:33], v[54:57], v[50:53], v[18:33]
	ds_read_b64_tr_b16 v[54:55], v114 offset:19328
	ds_read_b64_tr_b16 v[56:57], v114 offset:20992
	s_waitcnt lgkmcnt(0)
	s_barrier
	s_waitcnt vmcnt(0)
	ds_write_b128 v110, v[94:97]
	ds_write_b128 v110, v[90:93] offset:4608
	ds_write_b128 v119, v[86:89] offset:9216
	ds_write_b128 v120, v[82:85] offset:9216
	ds_write_b128 v121, v[78:81] offset:9216
	s_waitcnt lgkmcnt(0)
	s_barrier
	v_mfma_f32_32x32x16_bf16 v[2:17], v[54:57], v[50:53], v[2:17]
	ds_read_b128 v[50:53], v107
	ds_read_b128 v[78:81], v107 offset:32
	s_waitcnt lgkmcnt(1)
	v_mfma_f32_32x32x16_bf16 v[50:65], v[50:53], v[74:77], 0
	s_waitcnt lgkmcnt(0)
	v_mfma_f32_32x32x16_bf16 v[50:65], v[78:81], v[70:73], v[50:65]
	ds_read_b128 v[78:81], v107 offset:64
	s_waitcnt lgkmcnt(0)
	v_mfma_f32_32x32x16_bf16 v[50:65], v[78:81], v[66:69], v[50:65]
	v_subrev_u32_e32 v80, s68, v116
	v_add_u32_e32 v78, v108, v80
	v_cvt_f32_i32_e32 v79, v78
	v_cmp_gt_i32_e32 vcc, 0, v78
	v_mad_i32_i24 v81, v115, -4, s34
	v_readlane_b32 s34, v242, 36
	v_cndmask_b32_e64 v78, v112, -v113, vcc
	v_mul_f32_e32 v78, v78, v79
	v_add_u32_e32 v79, v108, v81
	v_cvt_f32_i32_e32 v82, v79
	v_cmp_gt_i32_e32 vcc, 0, v79
	v_exp_f32_e32 v78, v78
	s_nop 0
	v_cndmask_b32_e64 v79, v112, -v113, vcc
	v_mul_f32_e32 v79, v79, v82
	v_exp_f32_e32 v79, v79
	v_subrev_u32_e32 v82, s34, v116
	v_readlane_b32 s34, v242, 37
	v_pk_mul_f32 v[50:51], v[78:79], v[50:51]
	v_add_u32_e32 v78, v108, v82
	v_cvt_f32_i32_e32 v79, v78
	v_cmp_gt_i32_e32 vcc, 0, v78
	v_subrev_u32_e32 v83, s34, v116
	v_readlane_b32 s34, v242, 38
	v_cndmask_b32_e64 v78, v112, -v113, vcc
	v_mul_f32_e32 v78, v78, v79
	v_add_u32_e32 v79, v108, v83
	v_cvt_f32_i32_e32 v84, v79
	v_cmp_gt_i32_e32 vcc, 0, v79
	v_exp_f32_e32 v78, v78
	s_nop 0
	v_cndmask_b32_e64 v79, v112, -v113, vcc
	v_mul_f32_e32 v79, v79, v84
	v_exp_f32_e32 v79, v79
	s_nop 0
	v_pk_mul_f32 v[52:53], v[78:79], v[52:53]
	v_add_u32_e32 v78, v118, v80
	v_cvt_f32_i32_e32 v79, v78
	v_cmp_gt_i32_e32 vcc, 0, v78
	s_nop 1
	v_cndmask_b32_e64 v78, v112, -v113, vcc
	v_mul_f32_e32 v78, v78, v79
	v_add_u32_e32 v79, v118, v81
	v_cvt_f32_i32_e32 v84, v79
	v_cmp_gt_i32_e32 vcc, 0, v79
	v_exp_f32_e32 v78, v78
	s_nop 0
	v_cndmask_b32_e64 v79, v112, -v113, vcc
	v_mul_f32_e32 v79, v79, v84
	v_exp_f32_e32 v79, v79
	s_nop 0
	v_pk_mul_f32 v[54:55], v[78:79], v[54:55]
	v_add_u32_e32 v78, v118, v82
	v_cvt_f32_i32_e32 v79, v78
	v_cmp_gt_i32_e32 vcc, 0, v78
	s_nop 1
	v_cndmask_b32_e64 v78, v112, -v113, vcc
	v_mul_f32_e32 v78, v78, v79
	v_add_u32_e32 v79, v118, v83
	v_cvt_f32_i32_e32 v84, v79
	v_cmp_gt_i32_e32 vcc, 0, v79
	v_exp_f32_e32 v78, v78
	s_nop 0
	v_cndmask_b32_e64 v79, v112, -v113, vcc
	v_mul_f32_e32 v79, v79, v84
	v_exp_f32_e32 v79, v79
	s_nop 0
	v_pk_mul_f32 v[56:57], v[78:79], v[56:57]
	v_add_u32_e32 v78, v111, v80
	v_cvt_f32_i32_e32 v79, v78
	v_cmp_gt_i32_e32 vcc, 0, v78
	v_cvt_pk_bf16_f32 v85, v56, v57
	s_nop 0
	v_cndmask_b32_e64 v78, v112, -v113, vcc
	v_mul_f32_e32 v78, v78, v79
	v_add_u32_e32 v79, v111, v81
	v_cvt_f32_i32_e32 v84, v79
	v_cmp_gt_i32_e32 vcc, 0, v79
	v_exp_f32_e32 v78, v78
	s_nop 0
	v_cndmask_b32_e64 v79, v112, -v113, vcc
	v_mul_f32_e32 v79, v79, v84
	v_exp_f32_e32 v79, v79
	s_nop 0
	v_pk_mul_f32 v[58:59], v[78:79], v[58:59]
	v_add_u32_e32 v78, v111, v82
	v_cvt_f32_i32_e32 v79, v78
	v_cmp_gt_i32_e32 vcc, 0, v78
	s_nop 1
	v_cndmask_b32_e64 v78, v112, -v113, vcc
	v_mul_f32_e32 v78, v78, v79
	v_add_u32_e32 v79, v111, v83
	v_cvt_f32_i32_e32 v84, v79
	v_cmp_gt_i32_e32 vcc, 0, v79
	v_exp_f32_e32 v78, v78
	s_nop 0
	v_cndmask_b32_e64 v79, v112, -v113, vcc
	v_mul_f32_e32 v79, v79, v84
	v_exp_f32_e32 v79, v79
	v_cvt_pk_bf16_f32 v84, v54, v55
	v_pk_mul_f32 v[60:61], v[78:79], v[60:61]
	v_add_u32_e32 v78, v117, v80
	v_cvt_f32_i32_e32 v79, v78
	v_cmp_gt_i32_e32 vcc, 0, v78
	s_nop 1
	v_cndmask_b32_e64 v78, v112, -v113, vcc
	v_mul_f32_e32 v78, v78, v79
	v_add_u32_e32 v79, v117, v81
	v_cvt_f32_i32_e32 v80, v79
	v_cmp_gt_i32_e32 vcc, 0, v79
	v_exp_f32_e32 v78, v78
	s_nop 0
	v_cndmask_b32_e64 v79, v112, -v113, vcc
	v_mul_f32_e32 v79, v79, v80
	v_exp_f32_e32 v79, v79
	s_nop 0
	v_pk_mul_f32 v[62:63], v[78:79], v[62:63]
	v_add_u32_e32 v78, v117, v82
	v_cvt_f32_i32_e32 v79, v78
	v_cmp_gt_i32_e32 vcc, 0, v78
	v_cvt_pk_bf16_f32 v82, v50, v51
	s_nop 0
	v_cndmask_b32_e64 v78, v112, -v113, vcc
	v_mul_f32_e32 v78, v78, v79
	v_add_u32_e32 v79, v117, v83
	v_cvt_f32_i32_e32 v80, v79
	v_cvt_pk_bf16_f32 v83, v52, v53
	ds_read_b128 v[50:53], v107 offset:4608
	v_cmp_gt_i32_e32 vcc, 0, v79
	v_exp_f32_e32 v78, v78
	s_nop 0
	v_cndmask_b32_e64 v79, v112, -v113, vcc
	v_mul_f32_e32 v79, v79, v80
	v_exp_f32_e32 v79, v79
	v_cvt_pk_bf16_f32 v80, v62, v63
	v_pk_mul_f32 v[64:65], v[78:79], v[64:65]
	v_cvt_pk_bf16_f32 v78, v58, v59
	v_cvt_pk_bf16_f32 v79, v60, v61
	v_cvt_pk_bf16_f32 v81, v64, v65
	s_waitcnt lgkmcnt(0)
	v_mfma_f32_32x32x16_bf16 v[50:65], v[50:53], v[74:77], 0
	ds_read_b128 v[74:77], v107 offset:4640
	s_waitcnt lgkmcnt(0)
	v_mfma_f32_32x32x16_bf16 v[50:65], v[74:77], v[70:73], v[50:65]
	ds_read_b128 v[70:73], v107 offset:4672
	s_waitcnt lgkmcnt(0)
	v_mfma_f32_32x32x16_bf16 v[50:65], v[70:73], v[66:69], v[50:65]
	v_subrev_u32_e32 v70, s34, v116
	v_add_u32_e32 v66, v108, v70
	v_cvt_f32_i32_e32 v67, v66
	v_cmp_gt_i32_e32 vcc, 0, v66
	v_readlane_b32 s34, v242, 39
	v_subrev_u32_e32 v73, s69, v116
	v_cndmask_b32_e64 v66, v112, -v113, vcc
	v_subrev_u32_e32 v71, s34, v116
	v_mul_f32_e32 v66, v66, v67
	v_add_u32_e32 v67, v108, v71
	v_cvt_f32_i32_e32 v68, v67
	v_cmp_gt_i32_e32 vcc, 0, v67
	v_exp_f32_e32 v66, v66
	v_readlane_b32 s34, v242, 40
	v_cndmask_b32_e64 v67, v112, -v113, vcc
	v_mul_f32_e32 v67, v67, v68
	v_exp_f32_e32 v67, v67
	v_subrev_u32_e32 v72, s34, v116
	v_readlane_b32 s34, v242, 33
	v_readlane_b32 s35, v242, 34
	v_mov_b64_e32 v[132:133], s[28:29]
	v_lshl_add_u64 v[130:131], s[34:35], 0, v[108:109]
	s_nop 0
	v_mad_u64_u32 v[132:133], vcc, v130, s38, v[132:133]
	v_mad_i32_i24 v133, v131, s38, v133
	v_lshl_add_u64 v[132:133], v[132:133], 0, s[30:31]
	v_lshl_add_u64 v[132:133], v[132:133], 0, v[0:1]
	v_add_co_u32_e32 v130, vcc, 0x1000, v132
	s_nop 1
	v_addc_co_u32_e32 v131, vcc, 0, v133, vcc
	s_nop 0
	global_load_dwordx2 v[140:141], v[130:131], off offset:2816
	global_load_dwordx2 v[142:143], v[130:131], off offset:2832
	global_load_dwordx2 v[144:145], v[130:131], off offset:2848
	global_load_dwordx2 v[146:147], v[130:131], off offset:2864
	global_load_dwordx2 v[148:149], v[130:131], off offset:2880
	global_load_dwordx2 v[150:151], v[130:131], off offset:2896
	global_load_dwordx2 v[152:153], v[130:131], off offset:2912
	global_load_dwordx2 v[154:155], v[130:131], off offset:2928
	global_load_dwordx2 v[156:157], v[130:131], off offset:2944
	global_load_dwordx2 v[158:159], v[130:131], off offset:2960
	global_load_dwordx2 v[160:161], v[130:131], off offset:2976
	global_load_dwordx2 v[162:163], v[130:131], off offset:2992
	global_load_dwordx4 v[164:167], v106, s[6:7]
	global_load_dwordx4 v[168:171], v106, s[6:7] offset:32
	global_load_dwordx4 v[172:175], v106, s[6:7] offset:64
	global_load_dwordx4 v[176:179], v106, s[6:7] offset:96
	global_load_dwordx4 v[180:183], v106, s[6:7] offset:128
	global_load_dwordx4 v[184:187], v106, s[6:7] offset:160
	global_load_dwordx4 v[188:191], v106, s[6:7] offset:192
	global_load_dwordx4 v[192:195], v106, s[6:7] offset:224
	global_load_dwordx4 v[196:199], v106, s[6:7] offset:256
	global_load_dwordx4 v[132:135], v106, s[6:7] offset:288
	v_pk_mul_f32 v[50:51], v[66:67], v[50:51]
	v_add_u32_e32 v66, v108, v72
	v_cvt_f32_i32_e32 v67, v66
	v_cmp_gt_i32_e32 vcc, 0, v66
	s_nop 1
	v_cndmask_b32_e64 v66, v112, -v113, vcc
	v_mul_f32_e32 v66, v66, v67
	v_add_u32_e32 v67, v108, v73
	v_cvt_f32_i32_e32 v68, v67
	v_cmp_gt_i32_e32 vcc, 0, v67
	v_exp_f32_e32 v66, v66
	s_nop 0
	v_cndmask_b32_e64 v67, v112, -v113, vcc
	v_mul_f32_e32 v67, v67, v68
	v_exp_f32_e32 v67, v67
	s_nop 0
	v_pk_mul_f32 v[52:53], v[66:67], v[52:53]
	v_add_u32_e32 v66, v118, v70
	v_cvt_f32_i32_e32 v67, v66
	v_cmp_gt_i32_e32 vcc, 0, v66
	s_nop 1
	v_cndmask_b32_e64 v66, v112, -v113, vcc
	v_mul_f32_e32 v66, v66, v67
	v_add_u32_e32 v67, v118, v71
	v_cvt_f32_i32_e32 v68, v67
	v_cmp_gt_i32_e32 vcc, 0, v67
	v_exp_f32_e32 v66, v66
	s_nop 0
	v_cndmask_b32_e64 v67, v112, -v113, vcc
	v_mul_f32_e32 v67, v67, v68
	v_exp_f32_e32 v67, v67
	s_nop 0
	v_pk_mul_f32 v[66:67], v[66:67], v[54:55]
	v_add_u32_e32 v54, v118, v72
	v_cvt_f32_i32_e32 v55, v54
	v_cmp_gt_i32_e32 vcc, 0, v54
	s_nop 1
	v_cndmask_b32_e64 v54, v112, -v113, vcc
	v_mul_f32_e32 v54, v54, v55
	v_add_u32_e32 v55, v118, v73
	v_cvt_f32_i32_e32 v68, v55
	v_cmp_gt_i32_e32 vcc, 0, v55
	v_exp_f32_e32 v54, v54
	s_nop 0
	v_cndmask_b32_e64 v55, v112, -v113, vcc
	v_mul_f32_e32 v55, v55, v68
	v_exp_f32_e32 v55, v55
	s_nop 0
	v_pk_mul_f32 v[68:69], v[54:55], v[56:57]
	v_add_u32_e32 v54, v111, v70
	v_cvt_f32_i32_e32 v55, v54
	v_cmp_gt_i32_e32 vcc, 0, v54
	v_cvt_pk_bf16_f32 v57, v68, v69
	s_nop 0
	v_cndmask_b32_e64 v54, v112, -v113, vcc
	v_mul_f32_e32 v54, v54, v55
	v_add_u32_e32 v55, v111, v71
	v_cvt_f32_i32_e32 v56, v55
	v_cmp_gt_i32_e32 vcc, 0, v55
	v_exp_f32_e32 v54, v54
	s_nop 0
	v_cndmask_b32_e64 v55, v112, -v113, vcc
	v_mul_f32_e32 v55, v55, v56
	v_exp_f32_e32 v55, v55
	s_nop 0
	v_pk_mul_f32 v[58:59], v[54:55], v[58:59]
	v_add_u32_e32 v54, v111, v72
	v_cvt_f32_i32_e32 v55, v54
	v_cmp_gt_i32_e32 vcc, 0, v54
	s_nop 1
	v_cndmask_b32_e64 v54, v112, -v113, vcc
	v_mul_f32_e32 v54, v54, v55
	v_add_u32_e32 v55, v111, v73
	v_cvt_f32_i32_e32 v56, v55
	v_cmp_gt_i32_e32 vcc, 0, v55
	v_exp_f32_e32 v54, v54
	s_nop 0
	v_cndmask_b32_e64 v55, v112, -v113, vcc
	v_mul_f32_e32 v55, v55, v56
	v_exp_f32_e32 v55, v55
	s_nop 0
	v_pk_mul_f32 v[60:61], v[54:55], v[60:61]
	v_add_u32_e32 v54, v117, v70
	v_cvt_f32_i32_e32 v55, v54
	v_cmp_gt_i32_e32 vcc, 0, v54
	s_nop 1
	v_cndmask_b32_e64 v54, v112, -v113, vcc
	v_mul_f32_e32 v54, v54, v55
	v_add_u32_e32 v55, v117, v71
	v_cvt_f32_i32_e32 v56, v55
	v_cmp_gt_i32_e32 vcc, 0, v55
	v_exp_f32_e32 v54, v54
	s_nop 0
	v_cndmask_b32_e64 v55, v112, -v113, vcc
	v_mul_f32_e32 v55, v55, v56
	v_exp_f32_e32 v55, v55
	s_nop 0
	v_pk_mul_f32 v[62:63], v[54:55], v[62:63]
	v_add_u32_e32 v54, v117, v72
	v_cvt_f32_i32_e32 v55, v54
	v_cmp_gt_i32_e32 vcc, 0, v54
	s_nop 1
	v_cndmask_b32_e64 v54, v112, -v113, vcc
	v_mul_f32_e32 v54, v54, v55
	v_add_u32_e32 v55, v117, v73
	v_cvt_f32_i32_e32 v56, v55
	v_cmp_gt_i32_e32 vcc, 0, v55
	v_exp_f32_e32 v54, v54
	s_nop 0
	v_cndmask_b32_e64 v55, v112, -v113, vcc
	v_mul_f32_e32 v55, v55, v56
	v_exp_f32_e32 v55, v55
	v_cvt_pk_bf16_f32 v56, v66, v67
	v_pk_mul_f32 v[64:65], v[54:55], v[64:65]
	v_cvt_pk_bf16_f32 v54, v50, v51
	v_cvt_pk_bf16_f32 v50, v58, v59
	v_cvt_pk_bf16_f32 v51, v60, v61
	ds_read_b64_tr_b16 v[58:59], v114 offset:9216
	ds_read_b64_tr_b16 v[60:61], v114 offset:10880
	ds_read_b64_tr_b16 v[136:137], v114 offset:9280
	ds_read_b64_tr_b16 v[138:139], v114 offset:10944
	s_waitcnt lgkmcnt(2)
	v_mfma_f32_32x32x16_bf16 v[34:49], v[58:61], v[82:85], v[34:49]
	ds_read_b64_tr_b16 v[58:59], v114 offset:9344
	ds_read_b64_tr_b16 v[60:61], v114 offset:11008
	v_cvt_pk_bf16_f32 v55, v52, v53
	v_cvt_pk_bf16_f32 v52, v62, v63
	v_cvt_pk_bf16_f32 v53, v64, v65
	s_waitcnt lgkmcnt(2)
	v_mfma_f32_32x32x16_bf16 v[18:33], v[136:139], v[82:85], v[18:33]
	ds_read_b64_tr_b16 v[136:137], v114 offset:12544
	ds_read_b64_tr_b16 v[138:139], v114 offset:14208
	s_waitcnt lgkmcnt(2)
	v_mfma_f32_32x32x16_bf16 v[2:17], v[58:61], v[82:85], v[2:17]
	ds_read_b64_tr_b16 v[58:59], v114 offset:12608
	ds_read_b64_tr_b16 v[60:61], v114 offset:14272
	s_waitcnt lgkmcnt(2)
	v_mfma_f32_32x32x16_bf16 v[34:49], v[136:139], v[78:81], v[34:49]
	ds_read_b64_tr_b16 v[136:137], v114 offset:12672
	ds_read_b64_tr_b16 v[138:139], v114 offset:14336
	s_waitcnt lgkmcnt(2)
	v_mfma_f32_32x32x16_bf16 v[18:33], v[58:61], v[78:81], v[18:33]
	ds_read_b64_tr_b16 v[58:59], v114 offset:15872
	ds_read_b64_tr_b16 v[60:61], v114 offset:17536
	s_waitcnt lgkmcnt(2)
	v_mfma_f32_32x32x16_bf16 v[2:17], v[136:139], v[78:81], v[2:17]
	ds_read_b64_tr_b16 v[136:137], v114 offset:15936
	ds_read_b64_tr_b16 v[138:139], v114 offset:17600
	s_waitcnt lgkmcnt(2)
	v_mfma_f32_32x32x16_bf16 v[34:49], v[58:61], v[54:57], v[34:49]
	ds_read_b64_tr_b16 v[58:59], v114 offset:16000
	ds_read_b64_tr_b16 v[60:61], v114 offset:17664
	s_waitcnt lgkmcnt(2)
	v_mfma_f32_32x32x16_bf16 v[18:33], v[136:139], v[54:57], v[18:33]
	ds_read_b64_tr_b16 v[136:137], v114 offset:19200
	ds_read_b64_tr_b16 v[138:139], v114 offset:20864
	s_waitcnt lgkmcnt(2)
	v_mfma_f32_32x32x16_bf16 v[2:17], v[58:61], v[54:57], v[2:17]
	ds_read_b64_tr_b16 v[54:55], v114 offset:19264
	ds_read_b64_tr_b16 v[56:57], v114 offset:20928
	s_waitcnt lgkmcnt(2)
	v_mfma_f32_32x32x16_bf16 v[34:49], v[136:139], v[50:53], v[34:49]
	s_waitcnt lgkmcnt(0)
	v_mfma_f32_32x32x16_bf16 v[18:33], v[54:57], v[50:53], v[18:33]
	s_nop 7
	v_mul_f32_e32 v60, v35, v35
	v_fmac_f32_e32 v60, v34, v34
	v_fmac_f32_e32 v60, v36, v36
	v_fmac_f32_e32 v60, v37, v37
	v_fmac_f32_e32 v60, v38, v38
	v_fmac_f32_e32 v60, v39, v39
	v_fmac_f32_e32 v60, v40, v40
	v_fmac_f32_e32 v60, v41, v41
	v_fmac_f32_e32 v60, v42, v42
	v_fmac_f32_e32 v60, v43, v43
	v_fmac_f32_e32 v60, v44, v44
	v_fmac_f32_e32 v60, v45, v45
	v_fmac_f32_e32 v60, v46, v46
	v_fmac_f32_e32 v60, v47, v47
	v_fmac_f32_e32 v60, v48, v48
	v_fmac_f32_e32 v60, v49, v49
	v_fmac_f32_e32 v60, v18, v18
	v_fmac_f32_e32 v60, v19, v19
	v_fmac_f32_e32 v60, v20, v20
	ds_read_b64_tr_b16 v[54:55], v114 offset:19328
	ds_read_b64_tr_b16 v[56:57], v114 offset:20992
	v_fmac_f32_e32 v60, v21, v21
	v_fmac_f32_e32 v60, v22, v22
	v_fmac_f32_e32 v60, v23, v23
	v_fmac_f32_e32 v60, v24, v24
	v_fmac_f32_e32 v60, v25, v25
	s_waitcnt lgkmcnt(0)
	v_mfma_f32_32x32x16_bf16 v[2:17], v[54:57], v[50:53], v[2:17]
	global_load_dwordx4 v[66:69], v106, s[6:7] offset:320
	global_load_dwordx4 v[70:73], v106, s[6:7] offset:352
	v_fmac_f32_e32 v60, v26, v26
	v_fmac_f32_e32 v60, v27, v27
	v_fmac_f32_e32 v60, v28, v28
	v_fmac_f32_e32 v60, v29, v29
	v_fmac_f32_e32 v60, v30, v30
	v_fmac_f32_e32 v60, v31, v31
	v_fmac_f32_e32 v60, v32, v32
	v_fmac_f32_e32 v60, v33, v33
	s_nop 3
	v_fmac_f32_e32 v60, v2, v2
	v_fmac_f32_e32 v60, v3, v3
	v_fmac_f32_e32 v60, v4, v4
	v_fmac_f32_e32 v60, v5, v5
	v_fmac_f32_e32 v60, v6, v6
	v_fmac_f32_e32 v60, v7, v7
	v_pk_mul_f32 v[58:59], v[8:9], v[8:9]
	v_pk_mul_f32 v[56:57], v[10:11], v[10:11]
	v_add_f32_e32 v58, v58, v60
	v_add_f32_e32 v58, v59, v58
	v_add_f32_e32 v56, v56, v58
	v_pk_mul_f32 v[54:55], v[12:13], v[12:13]
	v_add_f32_e32 v56, v57, v56
	v_add_f32_e32 v54, v54, v56
	v_pk_mul_f32 v[52:53], v[14:15], v[14:15]
	v_add_f32_e32 v54, v55, v54
	v_add_f32_e32 v52, v52, v54
	v_pk_mul_f32 v[50:51], v[16:17], v[16:17]
	v_add_f32_e32 v52, v53, v52
	v_add_f32_e32 v50, v50, v52
	v_and_b32_e32 v52, 64, v211
	v_add_f32_e32 v50, v51, v50
	v_xor_b32_e32 v51, 32, v211
	v_add_u32_e32 v52, 64, v52
	v_cmp_lt_i32_e32 vcc, v51, v52
	v_lshl_add_u64 v[54:55], s[34:35], 0, v[108:109]
	v_mov_b64_e32 v[52:53], s[28:29]
	v_cndmask_b32_e32 v51, v211, v51, vcc
	v_lshlrev_b32_e32 v51, 2, v51
	ds_bpermute_b32 v51, v51, v50
	v_mad_u64_u32 v[52:53], s[28:29], v54, s38, v[52:53]
	v_mad_i32_i24 v53, v55, s38, v53
	v_lshl_add_u64 v[56:57], v[52:53], 0, s[30:31]
	s_waitcnt lgkmcnt(0)
	v_add_f32_e32 v50, v50, v51
	v_fmamk_f32 v50, v50, 0x3c2aaaab, v202
	v_cmp_gt_f32_e32 vcc, s74, v50
	v_mul_f32_e32 v51, 0x4b800000, v50
	v_lshlrev_b64 v[52:53], 4, v[54:55]
	v_cndmask_b32_e32 v50, v50, v51, vcc
	v_rsq_f32_e32 v50, v50
	v_mov_b32_e32 v55, v1
	v_lshl_add_u64 v[58:59], v[56:57], 0, v[0:1]
	v_and_b32_e32 v53, 0x1ffffff, v53
	v_mul_f32_e32 v51, 0x45800000, v50
	v_cndmask_b32_e32 v50, v50, v51, vcc
	v_lshlrev_b32_e32 v51, 6, v54
	v_and_b32_e32 v54, 64, v51
	v_lshl_add_u64 v[54:55], s[4:5], 0, v[54:55]
	s_mov_b64 s[4:5], 0x1b00
	v_lshl_add_u64 v[56:57], v[58:59], 0, s[4:5]
	v_add_co_u32_e32 v58, vcc, s36, v58
	v_pk_mul_f32 v[34:35], v[34:35], v[50:51] op_sel_hi:[1,0]
	s_nop 0
	v_addc_co_u32_e32 v59, vcc, 0, v59, vcc
	v_pk_mul_f32 v[36:37], v[36:37], v[50:51] op_sel_hi:[1,0]
	v_readlane_b32 s4, v242, 41
	v_and_b32_e32 v52, 0xffffffe0, v52
	v_readlane_b32 s5, v242, 42
	v_pk_mul_f32 v[38:39], v[38:39], v[50:51] op_sel_hi:[1,0]
	v_pk_mul_f32 v[18:19], v[18:19], v[50:51] op_sel_hi:[1,0]
	v_pk_mul_f32 v[20:21], v[20:21], v[50:51] op_sel_hi:[1,0]
	v_pk_mul_f32 v[22:23], v[22:23], v[50:51] op_sel_hi:[1,0]
	v_pk_mul_f32 v[2:3], v[2:3], v[50:51] op_sel_hi:[1,0]
	v_pk_mul_f32 v[4:5], v[4:5], v[50:51] op_sel_hi:[1,0]
	v_pk_mul_f32 v[6:7], v[6:7], v[50:51] op_sel_hi:[1,0]
	s_waitcnt vmcnt(11)
	v_pk_mul_f32 v[34:35], v[164:165], v[34:35]
	v_lshlrev_b32_e32 v58, 16, v140
	v_and_b32_e32 v59, 0xffff0000, v140
	v_pk_mul_f32 v[34:35], v[34:35], v[58:59]
	v_pk_mul_f32 v[36:37], v[166:167], v[36:37]
	v_lshlrev_b32_e32 v58, 16, v141
	v_and_b32_e32 v59, 0xffff0000, v141
	v_pk_mul_f32 v[36:37], v[36:37], v[58:59]
	v_cvt_pk_bf16_f32 v34, v34, v35
	v_cvt_pk_bf16_f32 v35, v36, v37
	v_lshl_add_u64 v[36:37], v[52:53], 0, s[4:5]
	v_lshlrev_b64 v[36:37], 7, v[36:37]
	v_lshl_add_u64 v[36:37], v[54:55], 0, v[36:37]
	v_lshl_add_u64 v[58:59], v[36:37], 0, v[0:1]
	global_store_dwordx2 v[58:59], v[34:35], off
	v_readlane_b32 s4, v242, 43
	v_readlane_b32 s5, v242, 44
	s_waitcnt vmcnt(11)
	v_pk_mul_f32 v[34:35], v[168:169], v[38:39]
	v_lshlrev_b32_e32 v38, 16, v142
	v_and_b32_e32 v39, 0xffff0000, v142
	v_pk_mul_f32 v[34:35], v[34:35], v[38:39]
	v_pk_mul_f32 v[38:39], v[40:41], v[50:51] op_sel_hi:[1,0]
	v_cvt_pk_bf16_f32 v34, v34, v35
	v_pk_mul_f32 v[36:37], v[170:171], v[38:39]
	v_lshlrev_b32_e32 v38, 16, v143
	v_and_b32_e32 v39, 0xffff0000, v143
	v_pk_mul_f32 v[36:37], v[36:37], v[38:39]
	v_pk_mul_f32 v[40:41], v[42:43], v[50:51] op_sel_hi:[1,0]
	v_cvt_pk_bf16_f32 v35, v36, v37
	global_store_dwordx2 v[58:59], v[34:35], off offset:16
	s_waitcnt vmcnt(11)
	v_pk_mul_f32 v[34:35], v[172:173], v[40:41]
	v_lshlrev_b32_e32 v40, 16, v144
	v_and_b32_e32 v41, 0xffff0000, v144
	v_pk_mul_f32 v[34:35], v[34:35], v[40:41]
	v_pk_mul_f32 v[40:41], v[44:45], v[50:51] op_sel_hi:[1,0]
	v_lshlrev_b32_e32 v38, 16, v145
	v_pk_mul_f32 v[36:37], v[174:175], v[40:41]
	v_and_b32_e32 v39, 0xffff0000, v145
	v_pk_mul_f32 v[36:37], v[36:37], v[38:39]
	v_cvt_pk_bf16_f32 v34, v34, v35
	v_cvt_pk_bf16_f32 v35, v36, v37
	global_store_dwordx2 v[58:59], v[34:35], off offset:32
	v_pk_mul_f32 v[40:41], v[46:47], v[50:51] op_sel_hi:[1,0]
	s_waitcnt vmcnt(11)
	v_pk_mul_f32 v[34:35], v[176:177], v[40:41]
	v_lshlrev_b32_e32 v40, 16, v146
	v_and_b32_e32 v41, 0xffff0000, v146
	v_pk_mul_f32 v[34:35], v[34:35], v[40:41]
	v_pk_mul_f32 v[40:41], v[48:49], v[50:51] op_sel_hi:[1,0]
	v_lshlrev_b32_e32 v38, 16, v147
	v_pk_mul_f32 v[36:37], v[178:179], v[40:41]
	v_and_b32_e32 v39, 0xffff0000, v147
	v_pk_mul_f32 v[36:37], v[36:37], v[38:39]
	v_cvt_pk_bf16_f32 v34, v34, v35
	v_cvt_pk_bf16_f32 v35, v36, v37
	global_store_dwordx2 v[58:59], v[34:35], off offset:48
	s_waitcnt vmcnt(11)
	v_pk_mul_f32 v[18:19], v[180:181], v[18:19]
	v_lshlrev_b32_e32 v34, 16, v148
	v_and_b32_e32 v35, 0xffff0000, v148
	v_pk_mul_f32 v[18:19], v[18:19], v[34:35]
	v_pk_mul_f32 v[20:21], v[182:183], v[20:21]
	v_lshlrev_b32_e32 v34, 16, v149
	v_and_b32_e32 v35, 0xffff0000, v149
	v_pk_mul_f32 v[20:21], v[20:21], v[34:35]
	v_cvt_pk_bf16_f32 v18, v18, v19
	v_cvt_pk_bf16_f32 v19, v20, v21
	v_lshl_add_u64 v[20:21], v[52:53], 0, s[4:5]
	v_lshlrev_b64 v[20:21], 7, v[20:21]
	v_lshl_add_u64 v[20:21], v[54:55], 0, v[20:21]
	v_lshl_add_u64 v[20:21], v[20:21], 0, v[0:1]
	global_store_dwordx2 v[20:21], v[18:19], off
	v_readlane_b32 s4, v242, 45
	v_readlane_b32 s5, v242, 46
	s_waitcnt vmcnt(11)
	v_pk_mul_f32 v[18:19], v[184:185], v[22:23]
	v_lshlrev_b32_e32 v22, 16, v150
	v_and_b32_e32 v23, 0xffff0000, v150
	v_pk_mul_f32 v[18:19], v[18:19], v[22:23]
	v_pk_mul_f32 v[22:23], v[24:25], v[50:51] op_sel_hi:[1,0]
	v_cvt_pk_bf16_f32 v18, v18, v19
	v_pk_mul_f32 v[20:21], v[186:187], v[22:23]
	v_lshlrev_b32_e32 v22, 16, v151
	v_and_b32_e32 v23, 0xffff0000, v151
	v_pk_mul_f32 v[20:21], v[20:21], v[22:23]
	v_pk_mul_f32 v[24:25], v[26:27], v[50:51] op_sel_hi:[1,0]
	v_cvt_pk_bf16_f32 v19, v20, v21
	v_lshl_add_u64 v[20:21], v[52:53], 0, s[4:5]
	v_lshlrev_b64 v[20:21], 7, v[20:21]
	v_lshl_add_u64 v[20:21], v[54:55], 0, v[20:21]
	v_lshl_add_u64 v[20:21], v[20:21], 0, v[0:1]
	global_store_dwordx2 v[20:21], v[18:19], off offset:16
	v_readlane_b32 s4, v242, 47
	v_readlane_b32 s5, v242, 48
	s_waitcnt vmcnt(11)
	v_pk_mul_f32 v[18:19], v[188:189], v[24:25]
	v_lshlrev_b32_e32 v24, 16, v152
	v_and_b32_e32 v25, 0xffff0000, v152
	v_pk_mul_f32 v[18:19], v[18:19], v[24:25]
	v_pk_mul_f32 v[24:25], v[28:29], v[50:51] op_sel_hi:[1,0]
	v_lshlrev_b32_e32 v22, 16, v153
	v_pk_mul_f32 v[20:21], v[190:191], v[24:25]
	v_and_b32_e32 v23, 0xffff0000, v153
	v_pk_mul_f32 v[20:21], v[20:21], v[22:23]
	v_cvt_pk_bf16_f32 v18, v18, v19
	v_cvt_pk_bf16_f32 v19, v20, v21
	v_lshl_add_u64 v[20:21], v[52:53], 0, s[4:5]
	v_lshlrev_b64 v[20:21], 7, v[20:21]
	v_lshl_add_u64 v[20:21], v[54:55], 0, v[20:21]
	v_lshl_add_u64 v[20:21], v[20:21], 0, v[0:1]
	global_store_dwordx2 v[20:21], v[18:19], off offset:32
	v_pk_mul_f32 v[24:25], v[30:31], v[50:51] op_sel_hi:[1,0]
	v_readlane_b32 s4, v242, 49
	v_readlane_b32 s5, v242, 50
	s_waitcnt vmcnt(11)
	v_pk_mul_f32 v[18:19], v[192:193], v[24:25]
	v_lshlrev_b32_e32 v24, 16, v154
	v_and_b32_e32 v25, 0xffff0000, v154
	v_pk_mul_f32 v[18:19], v[18:19], v[24:25]
	v_pk_mul_f32 v[24:25], v[32:33], v[50:51] op_sel_hi:[1,0]
	v_lshlrev_b32_e32 v22, 16, v155
	v_pk_mul_f32 v[20:21], v[194:195], v[24:25]
	v_and_b32_e32 v23, 0xffff0000, v155
	v_pk_mul_f32 v[20:21], v[20:21], v[22:23]
	v_cvt_pk_bf16_f32 v18, v18, v19
	v_cvt_pk_bf16_f32 v19, v20, v21
	v_lshl_add_u64 v[20:21], v[52:53], 0, s[4:5]
	v_lshlrev_b64 v[20:21], 7, v[20:21]
	v_lshl_add_u64 v[20:21], v[54:55], 0, v[20:21]
	v_lshl_add_u64 v[20:21], v[20:21], 0, v[0:1]
	global_store_dwordx2 v[20:21], v[18:19], off offset:48
	s_mov_b64 s[4:5], 0
	s_waitcnt vmcnt(11)
	v_pk_mul_f32 v[2:3], v[196:197], v[2:3]
	v_lshlrev_b32_e32 v18, 16, v156
	v_and_b32_e32 v19, 0xffff0000, v156
	v_pk_mul_f32 v[2:3], v[2:3], v[18:19]
	v_pk_mul_f32 v[4:5], v[198:199], v[4:5]
	v_lshlrev_b32_e32 v18, 16, v157
	v_and_b32_e32 v19, 0xffff0000, v157
	v_pk_mul_f32 v[4:5], v[4:5], v[18:19]
	v_cvt_pk_bf16_f32 v2, v2, v3
	v_cvt_pk_bf16_f32 v3, v4, v5
	v_lshl_add_u64 v[4:5], v[52:53], 0, s[92:93]
	v_lshlrev_b64 v[4:5], 7, v[4:5]
	v_lshl_add_u64 v[4:5], v[54:55], 0, v[4:5]
	v_lshl_add_u64 v[4:5], v[4:5], 0, v[0:1]
	global_store_dwordx2 v[4:5], v[2:3], off
	s_waitcnt vmcnt(11)
	v_pk_mul_f32 v[2:3], v[132:133], v[6:7]
	v_lshlrev_b32_e32 v6, 16, v158
	v_and_b32_e32 v7, 0xffff0000, v158
	v_pk_mul_f32 v[2:3], v[2:3], v[6:7]
	v_pk_mul_f32 v[6:7], v[8:9], v[50:51] op_sel_hi:[1,0]
	v_cvt_pk_bf16_f32 v2, v2, v3
	v_pk_mul_f32 v[4:5], v[134:135], v[6:7]
	v_lshlrev_b32_e32 v6, 16, v159
	v_and_b32_e32 v7, 0xffff0000, v159
	v_pk_mul_f32 v[4:5], v[4:5], v[6:7]
	v_pk_mul_f32 v[8:9], v[10:11], v[50:51] op_sel_hi:[1,0]
	v_cvt_pk_bf16_f32 v3, v4, v5
	v_lshl_add_u64 v[4:5], v[52:53], 0, s[94:95]
	v_lshlrev_b64 v[4:5], 7, v[4:5]
	v_lshl_add_u64 v[4:5], v[54:55], 0, v[4:5]
	v_lshl_add_u64 v[4:5], v[4:5], 0, v[0:1]
	global_store_dwordx2 v[4:5], v[2:3], off offset:16
	s_waitcnt vmcnt(11)
	v_pk_mul_f32 v[2:3], v[66:67], v[8:9]
	v_lshlrev_b32_e32 v8, 16, v160
	v_and_b32_e32 v9, 0xffff0000, v160
	v_pk_mul_f32 v[2:3], v[2:3], v[8:9]
	v_pk_mul_f32 v[8:9], v[12:13], v[50:51] op_sel_hi:[1,0]
	v_lshlrev_b32_e32 v6, 16, v161
	v_pk_mul_f32 v[4:5], v[68:69], v[8:9]
	v_and_b32_e32 v7, 0xffff0000, v161
	v_pk_mul_f32 v[4:5], v[4:5], v[6:7]
	v_cvt_pk_bf16_f32 v2, v2, v3
	v_cvt_pk_bf16_f32 v3, v4, v5
	v_lshl_add_u64 v[4:5], v[52:53], 0, s[96:97]
	v_lshlrev_b64 v[4:5], 7, v[4:5]
	v_lshl_add_u64 v[4:5], v[54:55], 0, v[4:5]
	v_lshl_add_u64 v[4:5], v[4:5], 0, v[0:1]
	global_store_dwordx2 v[4:5], v[2:3], off offset:32
	v_pk_mul_f32 v[8:9], v[14:15], v[50:51] op_sel_hi:[1,0]
	s_waitcnt vmcnt(11)
	v_pk_mul_f32 v[2:3], v[70:71], v[8:9]
	v_lshlrev_b32_e32 v8, 16, v162
	v_and_b32_e32 v9, 0xffff0000, v162
	v_pk_mul_f32 v[2:3], v[2:3], v[8:9]
	v_pk_mul_f32 v[8:9], v[16:17], v[50:51] op_sel_hi:[1,0]
	v_lshlrev_b32_e32 v6, 16, v163
	v_pk_mul_f32 v[4:5], v[72:73], v[8:9]
	v_and_b32_e32 v7, 0xffff0000, v163
	v_pk_mul_f32 v[4:5], v[4:5], v[6:7]
	v_cvt_pk_bf16_f32 v2, v2, v3
	v_cvt_pk_bf16_f32 v3, v4, v5
	v_lshl_add_u64 v[4:5], v[52:53], 0, s[2:3]
	v_lshlrev_b64 v[4:5], 7, v[4:5]
	v_lshl_add_u64 v[4:5], v[54:55], 0, v[4:5]
	v_lshl_add_u64 v[4:5], v[4:5], 0, v[0:1]
	global_store_dwordx2 v[4:5], v[2:3], off offset:48
	s_barrier
